# combo3 plus neighbourhood-attention bias LDS reads issued together per key row
# speedup vs baseline: 1.0226x; 1.0027x over previous
.LBB0_432:
	s_cmp_ge_u32 s33, s25
	s_cselect_b64 s[0:1], -1, 0
	s_cmp_lt_u32 s33, s29
	s_cselect_b64 s[38:39], -1, 0
	s_and_b64 s[0:1], s[0:1], s[38:39]
	s_andn2_b64 vcc, exec, s[0:1]
	s_cbranch_vccnz .LBB0_438
	ds_read_b128 v[34:37], v166
	ds_read_b128 v[50:53], v166 offset:4096
	ds_read_b128 v[90:93], v167
	s_mov_b64 s[0:1], -1
	s_andn2_b64 vcc, exec, s[14:15]
	v_add_u32_e32 v177, s31, v132
	v_add_u32_e32 v176, s31, v133
	v_add_u32_e32 v175, s31, v134
	v_add_u32_e32 v174, s31, v135
	s_waitcnt lgkmcnt(2)
	v_mfma_f32_32x32x16_bf16 v[34:49], v[34:37], v[74:77], 0
	v_add_u32_e32 v173, s31, v144
	v_add_u32_e32 v172, s31, v146
	v_add_u32_e32 v171, s31, v148
	v_add_u32_e32 v170, s31, v150
	s_waitcnt lgkmcnt(0)
	v_mfma_f32_32x32x16_bf16 v[34:49], v[90:93], v[66:69], v[34:49]
	ds_read_b128 v[90:93], v167 offset:4096
	v_mfma_f32_32x32x16_bf16 v[50:65], v[50:53], v[74:77], 0
	s_waitcnt lgkmcnt(0)
	v_mfma_f32_32x32x16_bf16 v[50:65], v[90:93], v[66:69], v[50:65]
	ds_read_b128 v[90:93], v168
	s_waitcnt lgkmcnt(0)
	v_mfma_f32_32x32x16_bf16 v[34:49], v[90:93], v[70:73], v[34:49]
	ds_read_b128 v[90:93], v168 offset:4096
	s_waitcnt lgkmcnt(0)
	v_mfma_f32_32x32x16_bf16 v[50:65], v[90:93], v[70:73], v[50:65]
	ds_read_b128 v[90:93], v169
	s_waitcnt lgkmcnt(0)
	v_mfma_f32_32x32x16_bf16 v[34:49], v[90:93], v[78:81], v[34:49]
	ds_read_b128 v[90:93], v169 offset:4096
	s_waitcnt lgkmcnt(0)
	v_mfma_f32_32x32x16_bf16 v[50:65], v[90:93], v[78:81], v[50:65]
	s_cbranch_vccnz .LBB0_435
	ds_read_b32 v212, v176 offset:25472
	ds_read_b32 v213, v177 offset:25472
	v_add_u32_e32 v214, s31, v151
	ds_read_b32 v214, v214 offset:25472
	ds_read_b32 v215, v175 offset:25472
	ds_read_b32 v216, v174 offset:25472
	v_add_u32_e32 v217, s31, v136
	ds_read_b32 v217, v217 offset:25472
	v_add_u32_e32 v218, s31, v137
	ds_read_b32 v218, v218 offset:25472
	v_add_u32_e32 v219, s31, v138
	ds_read_b32 v219, v219 offset:25472
	v_add_u32_e32 v220, s31, v139
	ds_read_b32 v220, v220 offset:25472
	v_add_u32_e32 v221, s31, v140
	ds_read_b32 v221, v221 offset:25472
	v_add_u32_e32 v222, s31, v141
	ds_read_b32 v222, v222 offset:25472
	v_add_u32_e32 v223, s31, v142
	ds_read_b32 v223, v223 offset:25472
	v_add_u32_e32 v224, s31, v143
	ds_read_b32 v224, v224 offset:25472
	ds_read_b32 v225, v173 offset:25472
	v_add_u32_e32 v226, s31, v145
	ds_read_b32 v226, v226 offset:25472
	ds_read_b32 v227, v172 offset:25472
	v_add_u32_e32 v228, s31, v147
	ds_read_b32 v228, v228 offset:25472
	ds_read_b32 v229, v171 offset:25472
	v_add_u32_e32 v230, s31, v149
	ds_read_b32 v230, v230 offset:25472
	ds_read_b32 v231, v170 offset:25472
	s_waitcnt lgkmcnt(0)
	v_mov_b32_e32 v91, v212
	v_add_u32_e32 v92, s31, v151
	v_mov_b32_e32 v90, v213
	s_mov_b64 s[0:1], 0
	v_mov_b32_e32 v92, v214
	s_waitcnt lgkmcnt(2)
	s_nop 4
	v_add_f32_e32 v91, v51, v91
	v_mul_f32_e32 v91, 0x3fb8aa3b, v91
	s_waitcnt lgkmcnt(0)
	v_add_f32_e32 v65, v65, v92
	v_exp_f32_e32 v99, v91
	v_mov_b32_e32 v91, v215
	v_mov_b32_e32 v92, 0
	v_mul_f32_e32 v65, 0x3fb8aa3b, v65
	s_waitcnt lgkmcnt(0)
	v_add_f32_e32 v91, v52, v91
	v_mul_f32_e32 v91, 0x3fb8aa3b, v91
	v_exp_f32_e32 v65, v65
	v_exp_f32_e32 v100, v91
	v_mov_b32_e32 v91, v216
	s_waitcnt lgkmcnt(0)
	v_add_f32_e32 v91, v53, v91
	v_mul_f32_e32 v91, 0x3fb8aa3b, v91
	s_nop 0
	v_exp_f32_e32 v101, v91
	v_add_u32_e32 v91, s31, v136
	v_mov_b32_e32 v91, v217
	s_waitcnt lgkmcnt(0)
	v_add_f32_e32 v54, v54, v91
	v_add_u32_e32 v91, s31, v137
	v_mov_b32_e32 v91, v218
	v_mul_f32_e32 v54, 0x3fb8aa3b, v54
	s_waitcnt lgkmcnt(0)
	v_add_f32_e32 v55, v55, v91
	v_add_u32_e32 v91, s31, v138
	v_mov_b32_e32 v91, v219
	v_exp_f32_e32 v54, v54
	v_mul_f32_e32 v55, 0x3fb8aa3b, v55
	s_waitcnt lgkmcnt(0)
	v_add_f32_e32 v56, v56, v91
	v_add_u32_e32 v91, s31, v139
	v_mov_b32_e32 v91, v220
	v_exp_f32_e32 v55, v55
	v_mul_f32_e32 v56, 0x3fb8aa3b, v56
	s_waitcnt lgkmcnt(0)
	v_add_f32_e32 v57, v57, v91
	v_mul_f32_e32 v57, 0x3fb8aa3b, v57
	v_exp_f32_e32 v56, v56
	v_exp_f32_e32 v102, v57
	v_add_u32_e32 v57, s31, v140
	v_mov_b32_e32 v57, v221
	s_waitcnt lgkmcnt(0)
	v_add_f32_e32 v57, v58, v57
	v_add_u32_e32 v58, s31, v141
	v_mov_b32_e32 v58, v222
	v_add_f32_e32 v90, v50, v90
	v_mul_f32_e32 v90, 0x3fb8aa3b, v90
	v_mul_f32_e32 v57, 0x3fb8aa3b, v57
	s_waitcnt lgkmcnt(0)
	v_add_f32_e32 v58, v59, v58
	v_add_u32_e32 v59, s31, v142
	v_mov_b32_e32 v59, v223
	v_exp_f32_e32 v98, v90
	v_mul_f32_e32 v58, 0x3fb8aa3b, v58
	v_exp_f32_e32 v57, v57
	s_waitcnt lgkmcnt(0)
	v_add_f32_e32 v59, v60, v59
	v_add_u32_e32 v60, s31, v143
	v_mov_b32_e32 v60, v224
	v_add_f32_e32 v90, 0, v98
	v_mul_f32_e32 v59, 0x3fb8aa3b, v59
	s_waitcnt lgkmcnt(0)
	v_add_f32_e32 v60, v61, v60
	v_mov_b32_e32 v61, v225
	v_add_f32_e32 v90, v90, v99
	v_exp_f32_e32 v58, v58
	v_add_f32_e32 v90, v90, v100
	s_waitcnt lgkmcnt(0)
	v_add_f32_e32 v61, v46, v61
	v_mul_f32_e32 v61, 0x3fb8aa3b, v61
	v_mul_f32_e32 v60, 0x3fb8aa3b, v60
	v_exp_f32_e32 v94, v61
	v_add_u32_e32 v61, s31, v145
	v_mov_b32_e32 v61, v226
	v_add_f32_e32 v90, v90, v101
	v_exp_f32_e32 v59, v59
	v_add_f32_e32 v90, v90, v54
	s_waitcnt lgkmcnt(0)
	v_add_f32_e32 v61, v62, v61
	v_mov_b32_e32 v62, v227
	v_mul_f32_e32 v61, 0x3fb8aa3b, v61
	v_add_f32_e32 v90, v90, v55
	s_waitcnt lgkmcnt(0)
	v_add_f32_e32 v62, v47, v62
	v_mul_f32_e32 v62, 0x3fb8aa3b, v62
	v_exp_f32_e32 v60, v60
	v_exp_f32_e32 v95, v62
	v_add_u32_e32 v62, s31, v147
	v_mov_b32_e32 v62, v228
	v_add_f32_e32 v90, v90, v56
	v_add_f32_e32 v91, 0, v94
	s_waitcnt lgkmcnt(0)
	v_add_f32_e32 v62, v63, v62
	v_mov_b32_e32 v63, v229
	v_add_f32_e32 v90, v90, v102
	v_exp_f32_e32 v61, v61
	v_add_f32_e32 v90, v90, v57
	s_waitcnt lgkmcnt(0)
	v_add_f32_e32 v63, v48, v63
	v_mul_f32_e32 v63, 0x3fb8aa3b, v63
	v_mul_f32_e32 v62, 0x3fb8aa3b, v62
	v_exp_f32_e32 v97, v63
	v_add_u32_e32 v63, s31, v149
	v_mov_b32_e32 v63, v230
	v_add_f32_e32 v90, v90, v58
	s_waitcnt lgkmcnt(0)
	v_add_f32_e32 v63, v64, v63
	v_mov_b32_e32 v64, v231
	v_add_f32_e32 v90, v90, v59
	v_exp_f32_e32 v62, v62
	v_add_f32_e32 v90, v90, v60
	v_mul_f32_e32 v63, 0x3fb8aa3b, v63
	s_waitcnt lgkmcnt(0)
	v_add_f32_e32 v64, v49, v64
	v_add_f32_e32 v90, v90, v61
	v_exp_f32_e32 v63, v63
	v_mul_f32_e32 v64, 0x3fb8aa3b, v64
	v_add_f32_e32 v90, v90, v62
	v_add_f32_e32 v91, v91, v95
	v_exp_f32_e32 v64, v64
	v_add_f32_e32 v90, v90, v63
	v_add_f32_e32 v91, v91, v97
	v_cvt_pk_bf16_f32 v96, v94, v95
	v_add_f32_e32 v90, v90, v65
	v_add_f32_e32 v91, v91, v64
	v_cvt_pk_bf16_f32 v97, v97, v64
	v_add_f32_e32 v90, v91, v90
	v_mov_b32_e32 v91, v90
	s_nop 1
	v_permlane32_swap_b32_e32 v90, v91
	v_add_f32_e32 v178, v90, v91
	v_mov_b32_e32 v90, 0
	s_nop 1
	v_permlane32_swap_b32_e32 v90, v92
	v_mov_b32_e32 v94, 0
	v_mov_b32_e32 v95, 0
	v_cvt_pk_bf16_f32 v98, v98, v99
	v_cvt_pk_bf16_f32 v99, v100, v101
	v_cvt_pk_bf16_f32 v100, v54, v55
	v_cvt_pk_bf16_f32 v101, v56, v102
	v_cvt_pk_bf16_f32 v102, v57, v58
	v_cvt_pk_bf16_f32 v103, v59, v60
	v_cvt_pk_bf16_f32 v104, v61, v62
	v_cvt_pk_bf16_f32 v105, v63, v65
	v_mov_b32_e32 v91, v90
	v_mov_b32_e32 v93, v92
	v_permlane32_swap_b32_e32 v94, v96
	v_permlane32_swap_b32_e32 v95, v97
	v_permlane32_swap_b32_e32 v98, v100
	v_permlane32_swap_b32_e32 v99, v101
	v_permlane32_swap_b32_e32 v102, v104
	v_permlane32_swap_b32_e32 v103, v105
.LBB0_435:
	s_andn2_b64 vcc, exec, s[0:1]
	s_cbranch_vccnz .LBB0_437
	v_add_u32_e32 v212, s31, v152
	ds_read_b32 v212, v212 offset:25472
	ds_read_b32 v213, v177 offset:25472
	v_add_u32_e32 v214, s31, v153
	ds_read_b32 v214, v214 offset:25472
	ds_read_b32 v215, v176 offset:25472
	v_add_u32_e32 v216, s31, v154
	ds_read_b32 v216, v216 offset:25472
	ds_read_b32 v217, v175 offset:25472
	v_add_u32_e32 v218, s31, v155
	ds_read_b32 v218, v218 offset:25472
	ds_read_b32 v219, v174 offset:25472
	v_add_u32_e32 v220, s31, v156
	ds_read_b32 v220, v220 offset:25472
	v_add_u32_e32 v221, s31, v157
	ds_read_b32 v221, v221 offset:25472
	v_add_u32_e32 v222, s31, v158
	ds_read_b32 v222, v222 offset:25472
	v_add_u32_e32 v223, s31, v159
	ds_read_b32 v223, v223 offset:25472
	v_add_u32_e32 v224, s31, v160
	ds_read_b32 v224, v224 offset:25472
	v_add_u32_e32 v225, s31, v161
	ds_read_b32 v225, v225 offset:25472
	v_add_u32_e32 v226, s31, v162
	ds_read_b32 v226, v226 offset:25472
	v_add_u32_e32 v227, s31, v163
	ds_read_b32 v227, v227 offset:25472
	ds_read_b32 v228, v173 offset:25472
	ds_read_b32 v229, v172 offset:25472
	ds_read_b32 v230, v171 offset:25472
	ds_read_b32 v231, v170 offset:25472
	s_waitcnt lgkmcnt(0)
	s_nop 8
	v_add_u32_e32 v54, s31, v152
	v_mov_b32_e32 v54, v212
	v_mov_b32_e32 v103, 0
	v_mov_b32_e32 v105, 0
	v_mov_b32_e32 v100, 0
	v_mov_b32_e32 v101, 0
	s_waitcnt lgkmcnt(0)
	v_add_f32_e32 v34, v34, v54
	v_mul_f32_e32 v34, 0x3fb8aa3b, v34
	v_permlane32_swap_b32_e32 v103, v105
	v_exp_f32_e32 v54, v34
	v_mov_b32_e32 v34, v213
	v_mov_b32_e32 v102, v103
	v_mov_b32_e32 v104, v105
	v_add_f32_e32 v55, 0, v54
	s_waitcnt lgkmcnt(0)
	v_add_f32_e32 v34, v50, v34
	v_add_u32_e32 v50, s31, v153
	v_mov_b32_e32 v50, v214
	v_mul_f32_e32 v34, 0x3fb8aa3b, v34
	s_waitcnt lgkmcnt(0)
	v_add_f32_e32 v35, v35, v50
	v_mul_f32_e32 v35, 0x3fb8aa3b, v35
	v_exp_f32_e32 v34, v34
	v_exp_f32_e32 v50, v35
	v_mov_b32_e32 v35, v215
	v_add_f32_e32 v56, 0, v34
	v_add_f32_e32 v55, v55, v50
	s_waitcnt lgkmcnt(0)
	v_add_f32_e32 v35, v51, v35
	v_add_u32_e32 v51, s31, v154
	v_mov_b32_e32 v51, v216
	v_mul_f32_e32 v35, 0x3fb8aa3b, v35
	v_cvt_pk_bf16_f32 v90, v54, v50
	s_waitcnt lgkmcnt(0)
	v_add_f32_e32 v36, v36, v51
	v_mul_f32_e32 v36, 0x3fb8aa3b, v36
	v_exp_f32_e32 v35, v35
	v_exp_f32_e32 v51, v36
	v_mov_b32_e32 v36, v217
	v_add_f32_e32 v56, v56, v35
	v_add_f32_e32 v55, v55, v51
	s_waitcnt lgkmcnt(0)
	v_add_f32_e32 v36, v52, v36
	v_add_u32_e32 v52, s31, v155
	v_mov_b32_e32 v52, v218
	v_mul_f32_e32 v36, 0x3fb8aa3b, v36
	v_cvt_pk_bf16_f32 v98, v34, v35
	s_waitcnt lgkmcnt(0)
	v_add_f32_e32 v37, v37, v52
	v_mul_f32_e32 v37, 0x3fb8aa3b, v37
	v_exp_f32_e32 v36, v36
	v_exp_f32_e32 v52, v37
	v_mov_b32_e32 v37, v219
	v_permlane32_swap_b32_e32 v98, v100
	v_add_f32_e32 v56, v56, v36
	s_waitcnt lgkmcnt(0)
	v_add_f32_e32 v37, v53, v37
	v_mul_f32_e32 v37, 0x3fb8aa3b, v37
	v_add_f32_e32 v55, v55, v52
	v_exp_f32_e32 v37, v37
	v_cvt_pk_bf16_f32 v91, v51, v52
	v_add_f32_e32 v53, v56, v37
	v_add_u32_e32 v56, s31, v156
	v_mov_b32_e32 v56, v220
	v_cvt_pk_bf16_f32 v99, v36, v37
	s_nop 1
	v_permlane32_swap_b32_e32 v99, v101
	s_waitcnt lgkmcnt(0)
	v_add_f32_e32 v38, v38, v56
	v_add_u32_e32 v56, s31, v157
	v_mov_b32_e32 v56, v221
	v_mul_f32_e32 v38, 0x3fb8aa3b, v38
	s_waitcnt lgkmcnt(0)
	v_add_f32_e32 v39, v39, v56
	v_add_u32_e32 v56, s31, v158
	v_mov_b32_e32 v56, v222
	v_exp_f32_e32 v38, v38
	v_mul_f32_e32 v39, 0x3fb8aa3b, v39
	s_waitcnt lgkmcnt(0)
	v_add_f32_e32 v40, v40, v56
	v_exp_f32_e32 v39, v39
	v_mul_f32_e32 v40, 0x3fb8aa3b, v40
	v_add_f32_e32 v55, v55, v38
	v_exp_f32_e32 v40, v40
	v_cvt_pk_bf16_f32 v92, v38, v39
	v_add_f32_e32 v55, v55, v39
	s_nop 0
	v_permlane32_swap_b32_e32 v90, v92
	v_add_f32_e32 v56, v55, v40
	v_add_u32_e32 v55, s31, v159
	v_mov_b32_e32 v55, v223
	s_waitcnt lgkmcnt(0)
	v_add_f32_e32 v41, v41, v55
	v_mul_f32_e32 v41, 0x3fb8aa3b, v41
	s_nop 0
	v_exp_f32_e32 v55, v41
	v_add_u32_e32 v41, s31, v160
	v_mov_b32_e32 v41, v224
	v_add_f32_e32 v56, v56, v55
	v_cvt_pk_bf16_f32 v93, v40, v55
	s_waitcnt lgkmcnt(0)
	v_add_f32_e32 v41, v42, v41
	v_add_u32_e32 v42, s31, v161
	v_mov_b32_e32 v42, v225
	v_mul_f32_e32 v41, 0x3fb8aa3b, v41
	v_permlane32_swap_b32_e32 v91, v93
	s_waitcnt lgkmcnt(0)
	v_add_f32_e32 v42, v43, v42
	v_add_u32_e32 v43, s31, v162
	v_mov_b32_e32 v43, v226
	v_exp_f32_e32 v41, v41
	v_mul_f32_e32 v42, 0x3fb8aa3b, v42
	s_waitcnt lgkmcnt(0)
	v_add_f32_e32 v43, v44, v43
	v_exp_f32_e32 v42, v42
	v_mul_f32_e32 v43, 0x3fb8aa3b, v43
	v_add_f32_e32 v56, v56, v41
	v_exp_f32_e32 v43, v43
	v_cvt_pk_bf16_f32 v94, v41, v42
	v_add_f32_e32 v56, v56, v42
	s_nop 0
	v_add_f32_e32 v44, v56, v43
	v_add_u32_e32 v56, s31, v163
	v_mov_b32_e32 v56, v227
	s_waitcnt lgkmcnt(0)
	v_add_f32_e32 v45, v45, v56
	v_mov_b32_e32 v56, v228
	v_mul_f32_e32 v45, 0x3fb8aa3b, v45
	s_waitcnt lgkmcnt(0)
	v_add_f32_e32 v46, v46, v56
	v_mov_b32_e32 v56, v229
	v_exp_f32_e32 v45, v45
	v_mul_f32_e32 v46, 0x3fb8aa3b, v46
	s_waitcnt lgkmcnt(0)
	v_add_f32_e32 v47, v47, v56
	v_mov_b32_e32 v56, v230
	v_exp_f32_e32 v46, v46
	v_mul_f32_e32 v47, 0x3fb8aa3b, v47
	v_add_f32_e32 v44, v44, v45
	s_waitcnt lgkmcnt(0)
	v_add_f32_e32 v48, v48, v56
	v_mov_b32_e32 v56, v231
	v_exp_f32_e32 v47, v47
	v_mul_f32_e32 v48, 0x3fb8aa3b, v48
	s_waitcnt lgkmcnt(0)
	v_add_f32_e32 v49, v49, v56
	v_add_f32_e32 v44, v44, v46
	v_exp_f32_e32 v48, v48
	v_mul_f32_e32 v49, 0x3fb8aa3b, v49
	v_cvt_pk_bf16_f32 v95, v43, v45
	v_add_f32_e32 v44, v44, v47
	v_exp_f32_e32 v49, v49
	v_cvt_pk_bf16_f32 v96, v46, v47
	v_add_f32_e32 v44, v44, v48
	v_cvt_pk_bf16_f32 v97, v48, v49
	v_add_f32_e32 v44, v44, v49
	v_permlane32_swap_b32_e32 v94, v96
	v_add_f32_e32 v44, v53, v44
	v_mov_b32_e32 v53, v44
	s_nop 1
	v_permlane32_swap_b32_e32 v44, v53
	v_add_f32_e32 v178, v44, v53
	v_permlane32_swap_b32_e32 v95, v97
